# out-proj residual epilogue: 16 loads in flight with counted vmcnt instead of load+vmcnt(0) per block
# speedup vs baseline: 1.0088x; 1.0088x over previous
.LBB0_485:
	v_lshl_add_u32 v148, s64, 8, v164
	v_lshl_or_b32 v146, s22, 8, v166
	v_mul_lo_u32 v147, v148, s6
	v_lshlrev_b32_e32 v158, 6, v148
	v_add_u32_e32 v147, v147, v146
	s_cmp_lt_i32 s64, s72
	s_cselect_b32 s91, s5, s49
	s_cselect_b32 s90, s4, s48
	v_lshlrev_b32_e32 v146, 2, v147
	v_lshlrev_b32_e32 v147, 1, v147
	s_mov_b64 s[82:83], s[20:21]
	s_lshl_b32 s44, s6, 5
	s_mul_i32 s45, s44, 5
	s_and_b64 vcc, exec, s[68:69]
	s_cbranch_vccnz .Lepr_bf16
	s_lshl_b32 s42, s6, 6
	s_mul_i32 s43, s42, 5
	s_lshl_b32 s0, s22, 4
	s_lshl_b32 s1, s17, 2
	s_add_i32 s0, s0, s1
	s_add_u32 s64, s50, s0
	s_addc_u32 s65, s51, 0
	global_load_dwordx4 v[128:131], v146, s[90:91]
	global_load_dwordx4 v[132:135], v146, s[90:91] offset:16
	global_load_dwordx4 v[148:151], v146, s[90:91] offset:512
	global_load_dwordx4 v[160:163], v146, s[90:91] offset:528
	s_add_u32 s90, s90, s42
	s_addc_u32 s91, s91, 0
	global_load_dwordx4 v[168:171], v146, s[90:91]
	global_load_dwordx4 v[172:175], v146, s[90:91] offset:16
	global_load_dwordx4 v[176:179], v146, s[90:91] offset:512
	global_load_dwordx4 v[194:197], v146, s[90:91] offset:528
	s_add_u32 s90, s90, s42
	s_addc_u32 s91, s91, 0
	global_load_dwordx4 v[202:205], v146, s[90:91]
	global_load_dwordx4 v[206:209], v146, s[90:91] offset:16
	global_load_dwordx4 v[210:213], v146, s[90:91] offset:512
	global_load_dwordx4 v[214:217], v146, s[90:91] offset:528
	s_add_u32 s90, s90, s42
	s_addc_u32 s91, s91, 0
	global_load_dwordx4 v[218:221], v146, s[90:91]
	global_load_dwordx4 v[222:225], v146, s[90:91] offset:16
	global_load_dwordx4 v[226:229], v146, s[90:91] offset:512
	global_load_dwordx4 v[230:233], v146, s[90:91] offset:528
	s_add_u32 s90, s90, s43
	s_addc_u32 s91, s91, 0
	v_xor_b32_e32 v159, 16, v199
	v_xor_b32_e32 v180, 32, v199
	v_lshlrev_b32_e32 v159, 2, v159
	v_lshlrev_b32_e32 v180, 2, v180
	s_waitcnt vmcnt(12)
	v_pk_add_f32 v[124:125], v[124:125], v[128:129]
	v_pk_add_f32 v[126:127], v[126:127], v[130:131]
	v_pk_add_f32 v[120:121], v[120:121], v[132:133]
	v_pk_add_f32 v[122:123], v[122:123], v[134:135]
	v_mul_f32_e32 v132, v125, v125
	v_mul_f32_e32 v133, v127, v127
	v_mul_f32_e32 v134, v121, v121
	v_mul_f32_e32 v135, v123, v123
	v_fmac_f32_e32 v132, v124, v124
	v_fmac_f32_e32 v133, v126, v126
	v_fmac_f32_e32 v134, v120, v120
	v_fmac_f32_e32 v135, v122, v122
	v_cvt_pk_bf16_f32 v128, v124, v125
	v_cvt_pk_bf16_f32 v129, v126, v127
	v_cvt_pk_bf16_f32 v130, v120, v121
	v_cvt_pk_bf16_f32 v131, v122, v123
	v_add_f32_e32 v132, v132, v133
	v_add_f32_e32 v134, v134, v135
	global_store_dwordx4 v147, v[128:131], s[82:83]
	v_add_f32_e32 v132, v132, v134
	v_pk_add_f32 v[116:117], v[116:117], v[148:149]
	v_pk_add_f32 v[118:119], v[118:119], v[150:151]
	v_pk_add_f32 v[112:113], v[112:113], v[160:161]
	v_pk_add_f32 v[114:115], v[114:115], v[162:163]
	v_mul_f32_e32 v160, v117, v117
	v_mul_f32_e32 v161, v119, v119
	v_mul_f32_e32 v162, v113, v113
	v_mul_f32_e32 v163, v115, v115
	v_fmac_f32_e32 v160, v116, v116
	v_fmac_f32_e32 v161, v118, v118
	v_fmac_f32_e32 v162, v112, v112
	v_fmac_f32_e32 v163, v114, v114
	v_cvt_pk_bf16_f32 v148, v116, v117
	v_cvt_pk_bf16_f32 v149, v118, v119
	v_cvt_pk_bf16_f32 v150, v112, v113
	v_cvt_pk_bf16_f32 v151, v114, v115
	v_add_f32_e32 v160, v160, v161
	v_add_f32_e32 v162, v162, v163
	global_store_dwordx4 v147, v[148:151], s[82:83] offset:256
	v_add_f32_e32 v160, v160, v162
	v_add_f32_e32 v132, v132, v160
	s_add_u32 s82, s82, s44
	s_addc_u32 s83, s83, 0
	global_load_dwordx4 v[124:127], v146, s[90:91]
	global_load_dwordx4 v[120:123], v146, s[90:91] offset:16
	global_load_dwordx4 v[116:119], v146, s[90:91] offset:512
	global_load_dwordx4 v[112:115], v146, s[90:91] offset:528
	s_add_u32 s90, s90, s42
	s_addc_u32 s91, s91, 0
	s_waitcnt vmcnt(14)
	v_pk_add_f32 v[108:109], v[108:109], v[168:169]
	v_pk_add_f32 v[110:111], v[110:111], v[170:171]
	v_pk_add_f32 v[104:105], v[104:105], v[172:173]
	v_pk_add_f32 v[106:107], v[106:107], v[174:175]
	v_mul_f32_e32 v172, v109, v109
	v_mul_f32_e32 v173, v111, v111
	v_mul_f32_e32 v174, v105, v105
	v_mul_f32_e32 v175, v107, v107
	v_fmac_f32_e32 v172, v108, v108
	v_fmac_f32_e32 v173, v110, v110
	v_fmac_f32_e32 v174, v104, v104
	v_fmac_f32_e32 v175, v106, v106
	v_cvt_pk_bf16_f32 v168, v108, v109
	v_cvt_pk_bf16_f32 v169, v110, v111
	v_cvt_pk_bf16_f32 v170, v104, v105
	v_cvt_pk_bf16_f32 v171, v106, v107
	v_add_f32_e32 v172, v172, v173
	v_add_f32_e32 v174, v174, v175
	global_store_dwordx4 v147, v[168:171], s[82:83]
	v_add_f32_e32 v172, v172, v174
	v_pk_add_f32 v[100:101], v[100:101], v[176:177]
	v_pk_add_f32 v[102:103], v[102:103], v[178:179]
	v_pk_add_f32 v[96:97], v[96:97], v[194:195]
	v_pk_add_f32 v[98:99], v[98:99], v[196:197]
	v_mul_f32_e32 v194, v101, v101
	v_mul_f32_e32 v195, v103, v103
	v_mul_f32_e32 v196, v97, v97
	v_mul_f32_e32 v197, v99, v99
	v_fmac_f32_e32 v194, v100, v100
	v_fmac_f32_e32 v195, v102, v102
	v_fmac_f32_e32 v196, v96, v96
	v_fmac_f32_e32 v197, v98, v98
	v_cvt_pk_bf16_f32 v176, v100, v101
	v_cvt_pk_bf16_f32 v177, v102, v103
	v_cvt_pk_bf16_f32 v178, v96, v97
	v_cvt_pk_bf16_f32 v179, v98, v99
	v_add_f32_e32 v194, v194, v195
	v_add_f32_e32 v196, v196, v197
	global_store_dwordx4 v147, v[176:179], s[82:83] offset:256
	v_add_f32_e32 v194, v194, v196
	v_add_f32_e32 v172, v172, v194
	s_add_u32 s82, s82, s44
	s_addc_u32 s83, s83, 0
	global_load_dwordx4 v[108:111], v146, s[90:91]
	global_load_dwordx4 v[104:107], v146, s[90:91] offset:16
	global_load_dwordx4 v[100:103], v146, s[90:91] offset:512
	global_load_dwordx4 v[96:99], v146, s[90:91] offset:528
	s_add_u32 s90, s90, s42
	s_addc_u32 s91, s91, 0
	s_waitcnt vmcnt(16)
	v_pk_add_f32 v[92:93], v[92:93], v[202:203]
	v_pk_add_f32 v[94:95], v[94:95], v[204:205]
	v_pk_add_f32 v[88:89], v[88:89], v[206:207]
	v_pk_add_f32 v[90:91], v[90:91], v[208:209]
	v_mul_f32_e32 v206, v93, v93
	v_mul_f32_e32 v207, v95, v95
	v_mul_f32_e32 v208, v89, v89
	v_mul_f32_e32 v209, v91, v91
	v_fmac_f32_e32 v206, v92, v92
	v_fmac_f32_e32 v207, v94, v94
	v_fmac_f32_e32 v208, v88, v88
	v_fmac_f32_e32 v209, v90, v90
	v_cvt_pk_bf16_f32 v202, v92, v93
	v_cvt_pk_bf16_f32 v203, v94, v95
	v_cvt_pk_bf16_f32 v204, v88, v89
	v_cvt_pk_bf16_f32 v205, v90, v91
	v_add_f32_e32 v206, v206, v207
	v_add_f32_e32 v208, v208, v209
	global_store_dwordx4 v147, v[202:205], s[82:83]
	v_add_f32_e32 v206, v206, v208
	v_pk_add_f32 v[84:85], v[84:85], v[210:211]
	v_pk_add_f32 v[86:87], v[86:87], v[212:213]
	v_pk_add_f32 v[80:81], v[80:81], v[214:215]
	v_pk_add_f32 v[82:83], v[82:83], v[216:217]
	v_mul_f32_e32 v214, v85, v85
	v_mul_f32_e32 v215, v87, v87
	v_mul_f32_e32 v216, v81, v81
	v_mul_f32_e32 v217, v83, v83
	v_fmac_f32_e32 v214, v84, v84
	v_fmac_f32_e32 v215, v86, v86
	v_fmac_f32_e32 v216, v80, v80
	v_fmac_f32_e32 v217, v82, v82
	v_cvt_pk_bf16_f32 v210, v84, v85
	v_cvt_pk_bf16_f32 v211, v86, v87
	v_cvt_pk_bf16_f32 v212, v80, v81
	v_cvt_pk_bf16_f32 v213, v82, v83
	v_add_f32_e32 v214, v214, v215
	v_add_f32_e32 v216, v216, v217
	global_store_dwordx4 v147, v[210:213], s[82:83] offset:256
	v_add_f32_e32 v214, v214, v216
	v_add_f32_e32 v206, v206, v214
	s_add_u32 s82, s82, s44
	s_addc_u32 s83, s83, 0
	global_load_dwordx4 v[92:95], v146, s[90:91]
	global_load_dwordx4 v[88:91], v146, s[90:91] offset:16
	global_load_dwordx4 v[84:87], v146, s[90:91] offset:512
	global_load_dwordx4 v[80:83], v146, s[90:91] offset:528
	s_add_u32 s90, s90, s42
	s_addc_u32 s91, s91, 0
	s_waitcnt vmcnt(18)
	v_pk_add_f32 v[76:77], v[76:77], v[218:219]
	v_pk_add_f32 v[78:79], v[78:79], v[220:221]
	v_pk_add_f32 v[72:73], v[72:73], v[222:223]
	v_pk_add_f32 v[74:75], v[74:75], v[224:225]
	v_mul_f32_e32 v222, v77, v77
	v_mul_f32_e32 v223, v79, v79
	v_mul_f32_e32 v224, v73, v73
	v_mul_f32_e32 v225, v75, v75
	v_fmac_f32_e32 v222, v76, v76
	v_fmac_f32_e32 v223, v78, v78
	v_fmac_f32_e32 v224, v72, v72
	v_fmac_f32_e32 v225, v74, v74
	v_cvt_pk_bf16_f32 v218, v76, v77
	v_cvt_pk_bf16_f32 v219, v78, v79
	v_cvt_pk_bf16_f32 v220, v72, v73
	v_cvt_pk_bf16_f32 v221, v74, v75
	v_add_f32_e32 v222, v222, v223
	v_add_f32_e32 v224, v224, v225
	global_store_dwordx4 v147, v[218:221], s[82:83]
	v_add_f32_e32 v222, v222, v224
	v_pk_add_f32 v[68:69], v[68:69], v[226:227]
	v_pk_add_f32 v[70:71], v[70:71], v[228:229]
	v_pk_add_f32 v[64:65], v[64:65], v[230:231]
	v_pk_add_f32 v[66:67], v[66:67], v[232:233]
	v_mul_f32_e32 v230, v69, v69
	v_mul_f32_e32 v231, v71, v71
	v_mul_f32_e32 v232, v65, v65
	v_mul_f32_e32 v233, v67, v67
	v_fmac_f32_e32 v230, v68, v68
	v_fmac_f32_e32 v231, v70, v70
	v_fmac_f32_e32 v232, v64, v64
	v_fmac_f32_e32 v233, v66, v66
	v_cvt_pk_bf16_f32 v226, v68, v69
	v_cvt_pk_bf16_f32 v227, v70, v71
	v_cvt_pk_bf16_f32 v228, v64, v65
	v_cvt_pk_bf16_f32 v229, v66, v67
	v_add_f32_e32 v230, v230, v231
	v_add_f32_e32 v232, v232, v233
	global_store_dwordx4 v147, v[226:229], s[82:83] offset:256
	v_add_f32_e32 v230, v230, v232
	v_add_f32_e32 v222, v222, v230
	s_add_u32 s82, s82, s45
	s_addc_u32 s83, s83, 0
	global_load_dwordx4 v[76:79], v146, s[90:91]
	global_load_dwordx4 v[72:75], v146, s[90:91] offset:16
	global_load_dwordx4 v[68:71], v146, s[90:91] offset:512
	global_load_dwordx4 v[64:67], v146, s[90:91] offset:528
	s_waitcnt vmcnt(18)
	v_pk_add_f32 v[60:61], v[60:61], v[124:125]
	v_pk_add_f32 v[62:63], v[62:63], v[126:127]
	v_pk_add_f32 v[56:57], v[56:57], v[120:121]
	v_pk_add_f32 v[58:59], v[58:59], v[122:123]
	v_mul_f32_e32 v120, v61, v61
	v_mul_f32_e32 v121, v63, v63
	v_mul_f32_e32 v122, v57, v57
	v_mul_f32_e32 v123, v59, v59
	v_fmac_f32_e32 v120, v60, v60
	v_fmac_f32_e32 v121, v62, v62
	v_fmac_f32_e32 v122, v56, v56
	v_fmac_f32_e32 v123, v58, v58
	v_cvt_pk_bf16_f32 v124, v60, v61
	v_cvt_pk_bf16_f32 v125, v62, v63
	v_cvt_pk_bf16_f32 v126, v56, v57
	v_cvt_pk_bf16_f32 v127, v58, v59
	v_add_f32_e32 v120, v120, v121
	v_add_f32_e32 v122, v122, v123
	global_store_dwordx4 v147, v[124:127], s[82:83]
	v_add_f32_e32 v120, v120, v122
	v_pk_add_f32 v[52:53], v[52:53], v[116:117]
	v_pk_add_f32 v[54:55], v[54:55], v[118:119]
	v_pk_add_f32 v[48:49], v[48:49], v[112:113]
	v_pk_add_f32 v[50:51], v[50:51], v[114:115]
	v_mul_f32_e32 v112, v53, v53
	v_mul_f32_e32 v113, v55, v55
	v_mul_f32_e32 v114, v49, v49
	v_mul_f32_e32 v115, v51, v51
	v_fmac_f32_e32 v112, v52, v52
	v_fmac_f32_e32 v113, v54, v54
	v_fmac_f32_e32 v114, v48, v48
	v_fmac_f32_e32 v115, v50, v50
	v_cvt_pk_bf16_f32 v116, v52, v53
	v_cvt_pk_bf16_f32 v117, v54, v55
	v_cvt_pk_bf16_f32 v118, v48, v49
	v_cvt_pk_bf16_f32 v119, v50, v51
	v_add_f32_e32 v112, v112, v113
	v_add_f32_e32 v114, v114, v115
	global_store_dwordx4 v147, v[116:119], s[82:83] offset:256
	v_add_f32_e32 v112, v112, v114
	v_add_f32_e32 v120, v120, v112
	s_add_u32 s82, s82, s44
	s_addc_u32 s83, s83, 0
	s_waitcnt vmcnt(14)
	v_pk_add_f32 v[44:45], v[44:45], v[108:109]
	v_pk_add_f32 v[46:47], v[46:47], v[110:111]
	v_pk_add_f32 v[40:41], v[40:41], v[104:105]
	v_pk_add_f32 v[42:43], v[42:43], v[106:107]
	v_mul_f32_e32 v104, v45, v45
	v_mul_f32_e32 v105, v47, v47
	v_mul_f32_e32 v106, v41, v41
	v_mul_f32_e32 v107, v43, v43
	v_fmac_f32_e32 v104, v44, v44
	v_fmac_f32_e32 v105, v46, v46
	v_fmac_f32_e32 v106, v40, v40
	v_fmac_f32_e32 v107, v42, v42
	v_cvt_pk_bf16_f32 v108, v44, v45
	v_cvt_pk_bf16_f32 v109, v46, v47
	v_cvt_pk_bf16_f32 v110, v40, v41
	v_cvt_pk_bf16_f32 v111, v42, v43
	v_add_f32_e32 v104, v104, v105
	v_add_f32_e32 v106, v106, v107
	global_store_dwordx4 v147, v[108:111], s[82:83]
	v_add_f32_e32 v104, v104, v106
	v_pk_add_f32 v[36:37], v[36:37], v[100:101]
	v_pk_add_f32 v[38:39], v[38:39], v[102:103]
	v_pk_add_f32 v[32:33], v[32:33], v[96:97]
	v_pk_add_f32 v[34:35], v[34:35], v[98:99]
	v_mul_f32_e32 v96, v37, v37
	v_mul_f32_e32 v97, v39, v39
	v_mul_f32_e32 v98, v33, v33
	v_mul_f32_e32 v99, v35, v35
	v_fmac_f32_e32 v96, v36, v36
	v_fmac_f32_e32 v97, v38, v38
	v_fmac_f32_e32 v98, v32, v32
	v_fmac_f32_e32 v99, v34, v34
	v_cvt_pk_bf16_f32 v100, v36, v37
	v_cvt_pk_bf16_f32 v101, v38, v39
	v_cvt_pk_bf16_f32 v102, v32, v33
	v_cvt_pk_bf16_f32 v103, v34, v35
	v_add_f32_e32 v96, v96, v97
	v_add_f32_e32 v98, v98, v99
	global_store_dwordx4 v147, v[100:103], s[82:83] offset:256
	v_add_f32_e32 v96, v96, v98
	v_add_f32_e32 v104, v104, v96
	s_add_u32 s82, s82, s44
	s_addc_u32 s83, s83, 0
	s_waitcnt vmcnt(10)
	v_pk_add_f32 v[28:29], v[28:29], v[92:93]
	v_pk_add_f32 v[30:31], v[30:31], v[94:95]
	v_pk_add_f32 v[24:25], v[24:25], v[88:89]
	v_pk_add_f32 v[26:27], v[26:27], v[90:91]
	v_mul_f32_e32 v88, v29, v29
	v_mul_f32_e32 v89, v31, v31
	v_mul_f32_e32 v90, v25, v25
	v_mul_f32_e32 v91, v27, v27
	v_fmac_f32_e32 v88, v28, v28
	v_fmac_f32_e32 v89, v30, v30
	v_fmac_f32_e32 v90, v24, v24
	v_fmac_f32_e32 v91, v26, v26
	v_cvt_pk_bf16_f32 v92, v28, v29
	v_cvt_pk_bf16_f32 v93, v30, v31
	v_cvt_pk_bf16_f32 v94, v24, v25
	v_cvt_pk_bf16_f32 v95, v26, v27
	v_add_f32_e32 v88, v88, v89
	v_add_f32_e32 v90, v90, v91
	global_store_dwordx4 v147, v[92:95], s[82:83]
	v_add_f32_e32 v88, v88, v90
	v_pk_add_f32 v[20:21], v[20:21], v[84:85]
	v_pk_add_f32 v[22:23], v[22:23], v[86:87]
	v_pk_add_f32 v[16:17], v[16:17], v[80:81]
	v_pk_add_f32 v[18:19], v[18:19], v[82:83]
	v_mul_f32_e32 v80, v21, v21
	v_mul_f32_e32 v81, v23, v23
	v_mul_f32_e32 v82, v17, v17
	v_mul_f32_e32 v83, v19, v19
	v_fmac_f32_e32 v80, v20, v20
	v_fmac_f32_e32 v81, v22, v22
	v_fmac_f32_e32 v82, v16, v16
	v_fmac_f32_e32 v83, v18, v18
	v_cvt_pk_bf16_f32 v84, v20, v21
	v_cvt_pk_bf16_f32 v85, v22, v23
	v_cvt_pk_bf16_f32 v86, v16, v17
	v_cvt_pk_bf16_f32 v87, v18, v19
	v_add_f32_e32 v80, v80, v81
	v_add_f32_e32 v82, v82, v83
	global_store_dwordx4 v147, v[84:87], s[82:83] offset:256
	v_add_f32_e32 v80, v80, v82
	v_add_f32_e32 v88, v88, v80
	s_add_u32 s82, s82, s44
	s_addc_u32 s83, s83, 0
	s_waitcnt vmcnt(6)
	v_pk_add_f32 v[12:13], v[12:13], v[76:77]
	v_pk_add_f32 v[14:15], v[14:15], v[78:79]
	v_pk_add_f32 v[8:9], v[8:9], v[72:73]
	v_pk_add_f32 v[10:11], v[10:11], v[74:75]
	v_mul_f32_e32 v72, v13, v13
	v_mul_f32_e32 v73, v15, v15
	v_mul_f32_e32 v74, v9, v9
	v_mul_f32_e32 v75, v11, v11
	v_fmac_f32_e32 v72, v12, v12
	v_fmac_f32_e32 v73, v14, v14
	v_fmac_f32_e32 v74, v8, v8
	v_fmac_f32_e32 v75, v10, v10
	v_cvt_pk_bf16_f32 v76, v12, v13
	v_cvt_pk_bf16_f32 v77, v14, v15
	v_cvt_pk_bf16_f32 v78, v8, v9
	v_cvt_pk_bf16_f32 v79, v10, v11
	v_add_f32_e32 v72, v72, v73
	v_add_f32_e32 v74, v74, v75
	global_store_dwordx4 v147, v[76:79], s[82:83]
	v_add_f32_e32 v72, v72, v74
	v_pk_add_f32 v[4:5], v[4:5], v[68:69]
	v_pk_add_f32 v[6:7], v[6:7], v[70:71]
	v_pk_add_f32 v[0:1], v[0:1], v[64:65]
	v_pk_add_f32 v[2:3], v[2:3], v[66:67]
	v_mul_f32_e32 v64, v5, v5
	v_mul_f32_e32 v65, v7, v7
	v_mul_f32_e32 v66, v1, v1
	v_mul_f32_e32 v67, v3, v3
	v_fmac_f32_e32 v64, v4, v4
	v_fmac_f32_e32 v65, v6, v6
	v_fmac_f32_e32 v66, v0, v0
	v_fmac_f32_e32 v67, v2, v2
	v_cvt_pk_bf16_f32 v68, v4, v5
	v_cvt_pk_bf16_f32 v69, v6, v7
	v_cvt_pk_bf16_f32 v70, v0, v1
	v_cvt_pk_bf16_f32 v71, v2, v3
	v_add_f32_e32 v64, v64, v65
	v_add_f32_e32 v66, v66, v67
	global_store_dwordx4 v147, v[68:71], s[82:83] offset:256
	v_add_f32_e32 v64, v64, v66
	v_add_f32_e32 v72, v72, v64
	ds_bpermute_b32 v161, v159, v132
	ds_bpermute_b32 v195, v159, v172
	ds_bpermute_b32 v215, v159, v206
	ds_bpermute_b32 v231, v159, v222
	ds_bpermute_b32 v113, v159, v120
	ds_bpermute_b32 v97, v159, v104
	ds_bpermute_b32 v81, v159, v88
	ds_bpermute_b32 v65, v159, v72
	s_waitcnt lgkmcnt(0)
	v_add_f32_e32 v132, v132, v161
	v_add_f32_e32 v172, v172, v195
	v_add_f32_e32 v206, v206, v215
	v_add_f32_e32 v222, v222, v231
	v_add_f32_e32 v120, v120, v113
	v_add_f32_e32 v104, v104, v97
	v_add_f32_e32 v88, v88, v81
	v_add_f32_e32 v72, v72, v65
	ds_bpermute_b32 v161, v180, v132
	ds_bpermute_b32 v195, v180, v172
	ds_bpermute_b32 v215, v180, v206
	ds_bpermute_b32 v231, v180, v222
	ds_bpermute_b32 v113, v180, v120
	ds_bpermute_b32 v97, v180, v104
	ds_bpermute_b32 v81, v180, v88
	ds_bpermute_b32 v65, v180, v72
	s_waitcnt lgkmcnt(0)
	v_add_f32_e32 v132, v132, v161
	v_add_f32_e32 v172, v172, v195
	v_add_f32_e32 v206, v206, v215
	v_add_f32_e32 v222, v222, v231
	v_add_f32_e32 v120, v120, v113
	v_add_f32_e32 v104, v104, v97
	v_add_f32_e32 v88, v88, v81
	v_add_f32_e32 v72, v72, v65
	s_and_saveexec_b64 s[0:1], s[38:39]
	global_store_dword v158, v132, s[64:65]
	global_store_dword v158, v172, s[64:65] offset:1024
	global_store_dword v158, v206, s[64:65] offset:2048
	global_store_dword v158, v222, s[64:65] offset:3072
	s_add_u32 s64, s64, 0x2000
	s_addc_u32 s65, s65, 0
	global_store_dword v158, v120, s[64:65]
	global_store_dword v158, v104, s[64:65] offset:1024
	global_store_dword v158, v88, s[64:65] offset:2048
	global_store_dword v158, v72, s[64:65] offset:3072
	s_or_b64 exec, exec, s[0:1]
	s_branch .LBB0_565
.Lepr_bf16:
	s_mov_b64 s[90:91], s[86:87]
	global_load_dwordx4 v[128:131], v147, s[90:91]
	global_load_dwordx4 v[132:135], v147, s[90:91] offset:256
	s_add_u32 s90, s90, s44
	s_addc_u32 s91, s91, 0
	global_load_dwordx4 v[148:151], v147, s[90:91]
	global_load_dwordx4 v[160:163], v147, s[90:91] offset:256
	s_add_u32 s90, s90, s44
	s_addc_u32 s91, s91, 0
	global_load_dwordx4 v[168:171], v147, s[90:91]
	global_load_dwordx4 v[172:175], v147, s[90:91] offset:256
	s_add_u32 s90, s90, s44
	s_addc_u32 s91, s91, 0
	global_load_dwordx4 v[176:179], v147, s[90:91]
	global_load_dwordx4 v[194:197], v147, s[90:91] offset:256
	s_add_u32 s90, s90, s45
	s_addc_u32 s91, s91, 0
	global_load_dwordx4 v[202:205], v147, s[90:91]
	global_load_dwordx4 v[206:209], v147, s[90:91] offset:256
	s_add_u32 s90, s90, s44
	s_addc_u32 s91, s91, 0
	global_load_dwordx4 v[210:213], v147, s[90:91]
	global_load_dwordx4 v[214:217], v147, s[90:91] offset:256
	s_add_u32 s90, s90, s44
	s_addc_u32 s91, s91, 0
	global_load_dwordx4 v[218:221], v147, s[90:91]
	global_load_dwordx4 v[222:225], v147, s[90:91] offset:256
	s_add_u32 s90, s90, s44
	s_addc_u32 s91, s91, 0
	global_load_dwordx4 v[226:229], v147, s[90:91]
	global_load_dwordx4 v[230:233], v147, s[90:91] offset:256
	s_waitcnt vmcnt(14)
	v_lshlrev_b32_e32 v234, 16, v128
	v_and_b32_e32 v235, 0xffff0000, v128
	v_lshlrev_b32_e32 v236, 16, v129
	v_and_b32_e32 v237, 0xffff0000, v129
	v_lshlrev_b32_e32 v238, 16, v130
	v_and_b32_e32 v239, 0xffff0000, v130
	v_lshlrev_b32_e32 v180, 16, v131
	v_and_b32_e32 v181, 0xffff0000, v131
	v_pk_add_f32 v[124:125], v[124:125], v[234:235]
	v_pk_add_f32 v[126:127], v[126:127], v[236:237]
	v_pk_add_f32 v[120:121], v[120:121], v[238:239]
	v_pk_add_f32 v[122:123], v[122:123], v[180:181]
	v_cvt_pk_bf16_f32 v128, v124, v125
	v_cvt_pk_bf16_f32 v129, v126, v127
	v_cvt_pk_bf16_f32 v130, v120, v121
	v_cvt_pk_bf16_f32 v131, v122, v123
	global_store_dwordx4 v147, v[128:131], s[82:83]
	v_lshlrev_b32_e32 v234, 16, v132
	v_and_b32_e32 v235, 0xffff0000, v132
	v_lshlrev_b32_e32 v236, 16, v133
	v_and_b32_e32 v237, 0xffff0000, v133
	v_lshlrev_b32_e32 v238, 16, v134
	v_and_b32_e32 v239, 0xffff0000, v134
	v_lshlrev_b32_e32 v180, 16, v135
	v_and_b32_e32 v181, 0xffff0000, v135
	v_pk_add_f32 v[116:117], v[116:117], v[234:235]
	v_pk_add_f32 v[118:119], v[118:119], v[236:237]
	v_pk_add_f32 v[112:113], v[112:113], v[238:239]
	v_pk_add_f32 v[114:115], v[114:115], v[180:181]
	v_cvt_pk_bf16_f32 v132, v116, v117
	v_cvt_pk_bf16_f32 v133, v118, v119
	v_cvt_pk_bf16_f32 v134, v112, v113
	v_cvt_pk_bf16_f32 v135, v114, v115
	global_store_dwordx4 v147, v[132:135], s[82:83] offset:256
	s_add_u32 s82, s82, s44
	s_addc_u32 s83, s83, 0
	s_waitcnt vmcnt(14)
	v_lshlrev_b32_e32 v234, 16, v148
	v_and_b32_e32 v235, 0xffff0000, v148
	v_lshlrev_b32_e32 v236, 16, v149
	v_and_b32_e32 v237, 0xffff0000, v149
	v_lshlrev_b32_e32 v238, 16, v150
	v_and_b32_e32 v239, 0xffff0000, v150
	v_lshlrev_b32_e32 v180, 16, v151
	v_and_b32_e32 v181, 0xffff0000, v151
	v_pk_add_f32 v[108:109], v[108:109], v[234:235]
	v_pk_add_f32 v[110:111], v[110:111], v[236:237]
	v_pk_add_f32 v[104:105], v[104:105], v[238:239]
	v_pk_add_f32 v[106:107], v[106:107], v[180:181]
	v_cvt_pk_bf16_f32 v148, v108, v109
	v_cvt_pk_bf16_f32 v149, v110, v111
	v_cvt_pk_bf16_f32 v150, v104, v105
	v_cvt_pk_bf16_f32 v151, v106, v107
	global_store_dwordx4 v147, v[148:151], s[82:83]
	v_lshlrev_b32_e32 v234, 16, v160
	v_and_b32_e32 v235, 0xffff0000, v160
	v_lshlrev_b32_e32 v236, 16, v161
	v_and_b32_e32 v237, 0xffff0000, v161
	v_lshlrev_b32_e32 v238, 16, v162
	v_and_b32_e32 v239, 0xffff0000, v162
	v_lshlrev_b32_e32 v180, 16, v163
	v_and_b32_e32 v181, 0xffff0000, v163
	v_pk_add_f32 v[100:101], v[100:101], v[234:235]
	v_pk_add_f32 v[102:103], v[102:103], v[236:237]
	v_pk_add_f32 v[96:97], v[96:97], v[238:239]
	v_pk_add_f32 v[98:99], v[98:99], v[180:181]
	v_cvt_pk_bf16_f32 v160, v100, v101
	v_cvt_pk_bf16_f32 v161, v102, v103
	v_cvt_pk_bf16_f32 v162, v96, v97
	v_cvt_pk_bf16_f32 v163, v98, v99
	global_store_dwordx4 v147, v[160:163], s[82:83] offset:256
	s_add_u32 s82, s82, s44
	s_addc_u32 s83, s83, 0
	s_waitcnt vmcnt(14)
	v_lshlrev_b32_e32 v234, 16, v168
	v_and_b32_e32 v235, 0xffff0000, v168
	v_lshlrev_b32_e32 v236, 16, v169
	v_and_b32_e32 v237, 0xffff0000, v169
	v_lshlrev_b32_e32 v238, 16, v170
	v_and_b32_e32 v239, 0xffff0000, v170
	v_lshlrev_b32_e32 v180, 16, v171
	v_and_b32_e32 v181, 0xffff0000, v171
	v_pk_add_f32 v[92:93], v[92:93], v[234:235]
	v_pk_add_f32 v[94:95], v[94:95], v[236:237]
	v_pk_add_f32 v[88:89], v[88:89], v[238:239]
	v_pk_add_f32 v[90:91], v[90:91], v[180:181]
	v_cvt_pk_bf16_f32 v168, v92, v93
	v_cvt_pk_bf16_f32 v169, v94, v95
	v_cvt_pk_bf16_f32 v170, v88, v89
	v_cvt_pk_bf16_f32 v171, v90, v91
	global_store_dwordx4 v147, v[168:171], s[82:83]
	v_lshlrev_b32_e32 v234, 16, v172
	v_and_b32_e32 v235, 0xffff0000, v172
	v_lshlrev_b32_e32 v236, 16, v173
	v_and_b32_e32 v237, 0xffff0000, v173
	v_lshlrev_b32_e32 v238, 16, v174
	v_and_b32_e32 v239, 0xffff0000, v174
	v_lshlrev_b32_e32 v180, 16, v175
	v_and_b32_e32 v181, 0xffff0000, v175
	v_pk_add_f32 v[84:85], v[84:85], v[234:235]
	v_pk_add_f32 v[86:87], v[86:87], v[236:237]
	v_pk_add_f32 v[80:81], v[80:81], v[238:239]
	v_pk_add_f32 v[82:83], v[82:83], v[180:181]
	v_cvt_pk_bf16_f32 v172, v84, v85
	v_cvt_pk_bf16_f32 v173, v86, v87
	v_cvt_pk_bf16_f32 v174, v80, v81
	v_cvt_pk_bf16_f32 v175, v82, v83
	global_store_dwordx4 v147, v[172:175], s[82:83] offset:256
	s_add_u32 s82, s82, s44
	s_addc_u32 s83, s83, 0
	s_waitcnt vmcnt(14)
	v_lshlrev_b32_e32 v234, 16, v176
	v_and_b32_e32 v235, 0xffff0000, v176
	v_lshlrev_b32_e32 v236, 16, v177
	v_and_b32_e32 v237, 0xffff0000, v177
	v_lshlrev_b32_e32 v238, 16, v178
	v_and_b32_e32 v239, 0xffff0000, v178
	v_lshlrev_b32_e32 v180, 16, v179
	v_and_b32_e32 v181, 0xffff0000, v179
	v_pk_add_f32 v[76:77], v[76:77], v[234:235]
	v_pk_add_f32 v[78:79], v[78:79], v[236:237]
	v_pk_add_f32 v[72:73], v[72:73], v[238:239]
	v_pk_add_f32 v[74:75], v[74:75], v[180:181]
	v_cvt_pk_bf16_f32 v176, v76, v77
	v_cvt_pk_bf16_f32 v177, v78, v79
	v_cvt_pk_bf16_f32 v178, v72, v73
	v_cvt_pk_bf16_f32 v179, v74, v75
	global_store_dwordx4 v147, v[176:179], s[82:83]
	v_lshlrev_b32_e32 v234, 16, v194
	v_and_b32_e32 v235, 0xffff0000, v194
	v_lshlrev_b32_e32 v236, 16, v195
	v_and_b32_e32 v237, 0xffff0000, v195
	v_lshlrev_b32_e32 v238, 16, v196
	v_and_b32_e32 v239, 0xffff0000, v196
	v_lshlrev_b32_e32 v180, 16, v197
	v_and_b32_e32 v181, 0xffff0000, v197
	v_pk_add_f32 v[68:69], v[68:69], v[234:235]
	v_pk_add_f32 v[70:71], v[70:71], v[236:237]
	v_pk_add_f32 v[64:65], v[64:65], v[238:239]
	v_pk_add_f32 v[66:67], v[66:67], v[180:181]
	v_cvt_pk_bf16_f32 v194, v68, v69
	v_cvt_pk_bf16_f32 v195, v70, v71
	v_cvt_pk_bf16_f32 v196, v64, v65
	v_cvt_pk_bf16_f32 v197, v66, v67
	global_store_dwordx4 v147, v[194:197], s[82:83] offset:256
	s_add_u32 s82, s82, s45
	s_addc_u32 s83, s83, 0
	s_waitcnt vmcnt(14)
	v_lshlrev_b32_e32 v234, 16, v202
	v_and_b32_e32 v235, 0xffff0000, v202
	v_lshlrev_b32_e32 v236, 16, v203
	v_and_b32_e32 v237, 0xffff0000, v203
	v_lshlrev_b32_e32 v238, 16, v204
	v_and_b32_e32 v239, 0xffff0000, v204
	v_lshlrev_b32_e32 v180, 16, v205
	v_and_b32_e32 v181, 0xffff0000, v205
	v_pk_add_f32 v[60:61], v[60:61], v[234:235]
	v_pk_add_f32 v[62:63], v[62:63], v[236:237]
	v_pk_add_f32 v[56:57], v[56:57], v[238:239]
	v_pk_add_f32 v[58:59], v[58:59], v[180:181]
	v_cvt_pk_bf16_f32 v202, v60, v61
	v_cvt_pk_bf16_f32 v203, v62, v63
	v_cvt_pk_bf16_f32 v204, v56, v57
	v_cvt_pk_bf16_f32 v205, v58, v59
	global_store_dwordx4 v147, v[202:205], s[82:83]
	v_lshlrev_b32_e32 v234, 16, v206
	v_and_b32_e32 v235, 0xffff0000, v206
	v_lshlrev_b32_e32 v236, 16, v207
	v_and_b32_e32 v237, 0xffff0000, v207
	v_lshlrev_b32_e32 v238, 16, v208
	v_and_b32_e32 v239, 0xffff0000, v208
	v_lshlrev_b32_e32 v180, 16, v209
	v_and_b32_e32 v181, 0xffff0000, v209
	v_pk_add_f32 v[52:53], v[52:53], v[234:235]
	v_pk_add_f32 v[54:55], v[54:55], v[236:237]
	v_pk_add_f32 v[48:49], v[48:49], v[238:239]
	v_pk_add_f32 v[50:51], v[50:51], v[180:181]
	v_cvt_pk_bf16_f32 v206, v52, v53
	v_cvt_pk_bf16_f32 v207, v54, v55
	v_cvt_pk_bf16_f32 v208, v48, v49
	v_cvt_pk_bf16_f32 v209, v50, v51
	global_store_dwordx4 v147, v[206:209], s[82:83] offset:256
	s_add_u32 s82, s82, s44
	s_addc_u32 s83, s83, 0
	s_waitcnt vmcnt(14)
	v_lshlrev_b32_e32 v234, 16, v210
	v_and_b32_e32 v235, 0xffff0000, v210
	v_lshlrev_b32_e32 v236, 16, v211
	v_and_b32_e32 v237, 0xffff0000, v211
	v_lshlrev_b32_e32 v238, 16, v212
	v_and_b32_e32 v239, 0xffff0000, v212
	v_lshlrev_b32_e32 v180, 16, v213
	v_and_b32_e32 v181, 0xffff0000, v213
	v_pk_add_f32 v[44:45], v[44:45], v[234:235]
	v_pk_add_f32 v[46:47], v[46:47], v[236:237]
	v_pk_add_f32 v[40:41], v[40:41], v[238:239]
	v_pk_add_f32 v[42:43], v[42:43], v[180:181]
	v_cvt_pk_bf16_f32 v210, v44, v45
	v_cvt_pk_bf16_f32 v211, v46, v47
	v_cvt_pk_bf16_f32 v212, v40, v41
	v_cvt_pk_bf16_f32 v213, v42, v43
	global_store_dwordx4 v147, v[210:213], s[82:83]
	v_lshlrev_b32_e32 v234, 16, v214
	v_and_b32_e32 v235, 0xffff0000, v214
	v_lshlrev_b32_e32 v236, 16, v215
	v_and_b32_e32 v237, 0xffff0000, v215
	v_lshlrev_b32_e32 v238, 16, v216
	v_and_b32_e32 v239, 0xffff0000, v216
	v_lshlrev_b32_e32 v180, 16, v217
	v_and_b32_e32 v181, 0xffff0000, v217
	v_pk_add_f32 v[36:37], v[36:37], v[234:235]
	v_pk_add_f32 v[38:39], v[38:39], v[236:237]
	v_pk_add_f32 v[32:33], v[32:33], v[238:239]
	v_pk_add_f32 v[34:35], v[34:35], v[180:181]
	v_cvt_pk_bf16_f32 v214, v36, v37
	v_cvt_pk_bf16_f32 v215, v38, v39
	v_cvt_pk_bf16_f32 v216, v32, v33
	v_cvt_pk_bf16_f32 v217, v34, v35
	global_store_dwordx4 v147, v[214:217], s[82:83] offset:256
	s_add_u32 s82, s82, s44
	s_addc_u32 s83, s83, 0
	s_waitcnt vmcnt(14)
	v_lshlrev_b32_e32 v234, 16, v218
	v_and_b32_e32 v235, 0xffff0000, v218
	v_lshlrev_b32_e32 v236, 16, v219
	v_and_b32_e32 v237, 0xffff0000, v219
	v_lshlrev_b32_e32 v238, 16, v220
	v_and_b32_e32 v239, 0xffff0000, v220
	v_lshlrev_b32_e32 v180, 16, v221
	v_and_b32_e32 v181, 0xffff0000, v221
	v_pk_add_f32 v[28:29], v[28:29], v[234:235]
	v_pk_add_f32 v[30:31], v[30:31], v[236:237]
	v_pk_add_f32 v[24:25], v[24:25], v[238:239]
	v_pk_add_f32 v[26:27], v[26:27], v[180:181]
	v_cvt_pk_bf16_f32 v218, v28, v29
	v_cvt_pk_bf16_f32 v219, v30, v31
	v_cvt_pk_bf16_f32 v220, v24, v25
	v_cvt_pk_bf16_f32 v221, v26, v27
	global_store_dwordx4 v147, v[218:221], s[82:83]
	v_lshlrev_b32_e32 v234, 16, v222
	v_and_b32_e32 v235, 0xffff0000, v222
	v_lshlrev_b32_e32 v236, 16, v223
	v_and_b32_e32 v237, 0xffff0000, v223
	v_lshlrev_b32_e32 v238, 16, v224
	v_and_b32_e32 v239, 0xffff0000, v224
	v_lshlrev_b32_e32 v180, 16, v225
	v_and_b32_e32 v181, 0xffff0000, v225
	v_pk_add_f32 v[20:21], v[20:21], v[234:235]
	v_pk_add_f32 v[22:23], v[22:23], v[236:237]
	v_pk_add_f32 v[16:17], v[16:17], v[238:239]
	v_pk_add_f32 v[18:19], v[18:19], v[180:181]
	v_cvt_pk_bf16_f32 v222, v20, v21
	v_cvt_pk_bf16_f32 v223, v22, v23
	v_cvt_pk_bf16_f32 v224, v16, v17
	v_cvt_pk_bf16_f32 v225, v18, v19
	global_store_dwordx4 v147, v[222:225], s[82:83] offset:256
	s_add_u32 s82, s82, s44
	s_addc_u32 s83, s83, 0
	s_waitcnt vmcnt(14)
	v_lshlrev_b32_e32 v234, 16, v226
	v_and_b32_e32 v235, 0xffff0000, v226
	v_lshlrev_b32_e32 v236, 16, v227
	v_and_b32_e32 v237, 0xffff0000, v227
	v_lshlrev_b32_e32 v238, 16, v228
	v_and_b32_e32 v239, 0xffff0000, v228
	v_lshlrev_b32_e32 v180, 16, v229
	v_and_b32_e32 v181, 0xffff0000, v229
	v_pk_add_f32 v[12:13], v[12:13], v[234:235]
	v_pk_add_f32 v[14:15], v[14:15], v[236:237]
	v_pk_add_f32 v[8:9], v[8:9], v[238:239]
	v_pk_add_f32 v[10:11], v[10:11], v[180:181]
	v_cvt_pk_bf16_f32 v226, v12, v13
	v_cvt_pk_bf16_f32 v227, v14, v15
	v_cvt_pk_bf16_f32 v228, v8, v9
	v_cvt_pk_bf16_f32 v229, v10, v11
	global_store_dwordx4 v147, v[226:229], s[82:83]
	v_lshlrev_b32_e32 v234, 16, v230
	v_and_b32_e32 v235, 0xffff0000, v230
	v_lshlrev_b32_e32 v236, 16, v231
	v_and_b32_e32 v237, 0xffff0000, v231
	v_lshlrev_b32_e32 v238, 16, v232
	v_and_b32_e32 v239, 0xffff0000, v232
	v_lshlrev_b32_e32 v180, 16, v233
	v_and_b32_e32 v181, 0xffff0000, v233
	v_pk_add_f32 v[4:5], v[4:5], v[234:235]
	v_pk_add_f32 v[6:7], v[6:7], v[236:237]
	v_pk_add_f32 v[0:1], v[0:1], v[238:239]
	v_pk_add_f32 v[2:3], v[2:3], v[180:181]
	v_cvt_pk_bf16_f32 v230, v4, v5
	v_cvt_pk_bf16_f32 v231, v6, v7
	v_cvt_pk_bf16_f32 v232, v0, v1
	v_cvt_pk_bf16_f32 v233, v2, v3
	global_store_dwordx4 v147, v[230:233], s[82:83] offset:256
.LBB0_565:
	s_and_b64 vcc, exec, s[40:41]
	s_mov_b64 s[0:1], -1
	s_cbranch_vccnz .LBB0_467
	s_andn2_b64 vcc, exec, s[60:61]
	s_cbranch_vccnz .LBB0_466
	s_barrier
	s_branch .LBB0_466
.LBB0_584:
	s_branch .LBB0_471
